# MLA tile loop hand rewrite: persistent -mrun splat, no score copies, K1 reads after 2 MFMAs, max3 chains, PV interleaved with exps, waves 0-3 run softmax+PV half a tile late
# baseline (speedup 1.0000x reference)
.LBB0_763:
	s_or_b64 exec, exec, s[0:1]
	s_lshl_b32 s0, s97, 16
	v_readlane_b32 s1, v247, 30
	s_add_u32 s0, s1, s0
	v_readlane_b32 s1, v247, 31
	s_addc_u32 s1, s1, 0
	s_lshl_b32 s11, s12, 1
	s_add_u32 s0, s0, s11
	s_addc_u32 s1, s1, 0
	v_lshlrev_b32_e32 v2, 1, v146
	v_mov_b32_e32 v3, v17
	v_lshl_add_u64 v[2:3], s[0:1], 0, v[2:3]
	v_lshl_add_u64 v[2:3], v[2:3], 0, v[16:17]
	global_load_dwordx4 v[2:5], v[2:3], off
	v_add_u32_e32 v177, v213, v144
	ds_read_b128 v[34:37], v177
	ds_read_b128 v[38:41], v177 offset:32
	ds_read_b128 v[42:45], v177 offset:64
	ds_read_b128 v[46:49], v177 offset:96
	ds_read_b128 v[66:69], v177 offset:128
	ds_read_b128 v[70:73], v177 offset:160
	v_mov_b32_e32 v51, v50
	v_mov_b32_e32 v52, v50
	v_mov_b32_e32 v53, v50
	v_mov_b32_e32 v54, v50
	v_mov_b32_e32 v55, v50
	v_mov_b32_e32 v56, v50
	v_mov_b32_e32 v57, v50
	v_mov_b32_e32 v58, v50
	v_mov_b32_e32 v59, v50
	v_mov_b32_e32 v60, v50
	v_mov_b32_e32 v61, v50
	v_mov_b32_e32 v62, v50
	v_mov_b32_e32 v63, v50
	v_mov_b32_e32 v64, v50
	v_mov_b32_e32 v65, v50
	v_mov_b64_e32 v[18:19], v[50:51]
	v_mov_b64_e32 v[20:21], v[52:53]
	v_mov_b64_e32 v[22:23], v[54:55]
	v_mov_b64_e32 v[24:25], v[56:57]
	v_mov_b64_e32 v[26:27], v[58:59]
	v_mov_b64_e32 v[28:29], v[60:61]
	v_mov_b64_e32 v[30:31], v[62:63]
	v_mov_b64_e32 v[32:33], v[64:65]
	v_add_u32_e32 v51, v214, v210
	ds_read_b128 v[52:55], v51 offset:13312
	ds_read_b128 v[90:93], v51 offset:13344
	ds_read_b128 v[94:97], v51 offset:17920
	ds_read_b128 v[98:101], v51 offset:17952
	s_waitcnt lgkmcnt(9)
	v_mfma_f32_32x32x16_bf16 v[18:33], v[34:37], v[124:127], v[18:33]
	s_waitcnt lgkmcnt(8)
	v_mfma_f32_32x32x16_bf16 v[18:33], v[38:41], v[120:123], v[18:33]
	s_waitcnt lgkmcnt(7)
	v_mfma_f32_32x32x16_bf16 v[18:33], v[42:45], v[116:119], v[18:33]
	s_waitcnt lgkmcnt(6)
	v_mfma_f32_32x32x16_bf16 v[18:33], v[46:49], v[112:115], v[18:33]
	s_waitcnt lgkmcnt(5)
	v_mfma_f32_32x32x16_bf16 v[18:33], v[66:69], v[108:111], v[18:33]
	s_waitcnt lgkmcnt(4)
	v_mfma_f32_32x32x16_bf16 v[18:33], v[70:73], v[104:107], v[18:33]
	s_nop 11
	v_max_f32_e32 v10, v18, v18
	v_max_f32_e32 v10, 0xf149f2ca, v10
	v_max3_f32 v10, v10, v19, v20
	v_max3_f32 v10, v10, v21, v22
	v_max3_f32 v10, v10, v23, v24
	v_max3_f32 v10, v10, v25, s86
	v_mov_b32_e32 v12, v10
	v_mov_b32_e32 v13, v10
	s_nop 1
	v_permlane32_swap_b32_e32 v12, v13
	v_cndmask_b32_e64 v12, v12, v13, s[6:7]
	v_max_f32_e32 v12, v12, v12
	v_max_f32_e32 v10, v10, v12
	v_exp_f32_e64 v12, -v10
	v_sub_f32_e32 v13, v19, v10
	v_sub_f32_e32 v16, v20, v10
	v_sub_f32_e32 v19, v22, v10
	v_mul_f32_e32 v32, 0, v12
	v_sub_f32_e32 v12, v18, v10
	v_sub_f32_e32 v18, v21, v10
	v_sub_f32_e32 v20, v23, v10
	v_sub_f32_e32 v21, v24, v10
	v_sub_f32_e32 v22, v25, v10
	v_exp_f32_e32 v12, v12
	v_exp_f32_e32 v13, v13
	v_exp_f32_e32 v48, v16
	v_exp_f32_e32 v49, v18
	v_exp_f32_e32 v84, v19
	v_exp_f32_e32 v85, v20
	v_exp_f32_e32 v86, v21
	v_exp_f32_e32 v87, v22
	v_mov_b32_e32 v33, v32
	v_mov_b32_e32 v34, v32
	v_mov_b32_e32 v35, v32
	v_mov_b32_e32 v36, v32
	v_mov_b32_e32 v37, v32
	v_mov_b32_e32 v38, v32
	v_mov_b32_e32 v39, v32
	v_mov_b32_e32 v40, v32
	v_mov_b32_e32 v41, v32
	v_mov_b32_e32 v42, v32
	v_mov_b32_e32 v43, v32
	v_mov_b32_e32 v44, v32
	v_mov_b32_e32 v45, v32
	v_mov_b32_e32 v46, v32
	v_mov_b32_e32 v47, v32
	v_cvt_pk_bf16_f32 v18, v12, v13
	v_cvt_pk_bf16_f32 v19, v48, v49
	v_cvt_pk_bf16_f32 v20, v84, v85
	v_cvt_pk_bf16_f32 v21, v86, v87
	v_sub_f32_e32 v16, 0xf149f2ca, v10
	s_waitcnt vmcnt(1)
	ds_write_b128 v89, v[6:9] offset:22528
	s_waitcnt lgkmcnt(4)
	v_mfma_f32_32x32x16_bf16 v[68:83], v[52:55], v[18:21], v[32:47]
	v_mov_b64_e32 v[66:67], v[46:47]
	v_mov_b64_e32 v[64:65], v[44:45]
	v_mov_b64_e32 v[62:63], v[42:43]
	v_mov_b64_e32 v[60:61], v[40:41]
	v_mov_b64_e32 v[58:59], v[38:39]
	v_mov_b64_e32 v[56:57], v[36:37]
	v_mov_b64_e32 v[54:55], v[34:35]
	v_mov_b64_e32 v[52:53], v[32:33]
	v_exp_f32_e32 v34, v16
	s_waitcnt lgkmcnt(2)
	v_mfma_f32_32x32x16_bf16 v[52:67], v[94:97], v[18:21], v[52:67]
	v_cvt_pk_bf16_f32 v18, v34, v34
	v_mov_b32_e32 v19, v18
	v_mov_b32_e32 v20, v18
	v_mov_b32_e32 v21, v18
	s_nop 1
	v_mfma_f32_32x32x16_bf16 v[68:83], v[90:93], v[18:21], v[68:83]
	s_waitcnt lgkmcnt(1)
	v_mfma_f32_32x32x16_bf16 v[52:67], v[98:101], v[18:21], v[52:67]
	s_and_saveexec_b64 s[0:1], s[2:3]
	ds_write_b128 v11, v[128:131] offset:22656
	s_or_b64 exec, exec, s[0:1]
	v_pk_add_f32 v[6:7], v[12:13], 0 op_sel_hi:[1,0]
	s_bfe_u32 s25, s84, 0x4000b
	v_pk_add_f32 v[6:7], v[48:49], v[6:7]
	v_mad_u64_u32 v[184:185], s[0:1], s25, v221, v[168:169]
	v_pk_add_f32 v[6:7], v[84:85], v[6:7]
	v_mov_b32_e32 v18, v17
	v_pk_add_f32 v[6:7], v[86:87], v[6:7]
	v_mov_b32_e32 v19, v17
	v_pk_add_f32 v[6:7], v[34:35], v[6:7] op_sel_hi:[0,1]
	v_pk_add_f32 v[6:7], v[34:35], v[6:7] op_sel_hi:[0,1]
	v_pk_add_f32 v[6:7], v[34:35], v[6:7] op_sel_hi:[0,1]
	v_pk_add_f32 v[6:7], v[34:35], v[6:7] op_sel_hi:[0,1]
	v_pk_add_f32 v[6:7], v[6:7], v[6:7] op_sel_hi:[0,1]
	v_mov_b32_e32 v20, v17
	v_mov_b32_e32 v21, v17
	v_mov_b32_e32 v22, v17
	v_mov_b32_e32 v23, v17
	v_mov_b32_e32 v24, v17
	v_mov_b32_e32 v25, v17
	v_mov_b32_e32 v26, v17
	v_mov_b32_e32 v27, v17
	v_mov_b32_e32 v28, v17
	v_mov_b32_e32 v29, v17
	v_mov_b32_e32 v30, v17
	v_mov_b32_e32 v31, v17
	v_mov_b32_e32 v11, v32
	v_mov_b32_e32 v6, v17
	s_lshl_b32 s30, s16, 3
	s_lshl_b32 s0, s25, 21
	s_lshl_b32 s1, s17, 7
	v_mov_b32_e32 v16, v17
	v_pk_add_f32 v[182:183], v[10:11], v[6:7]
	s_add_i32 s11, s24, s30
	s_or_b32 s0, s0, s1
	s_mov_b32 s1, s9
	v_add_u32_e32 v6, 0x8800, v88
	s_waitcnt vmcnt(0)
	v_mov_b64_e32 v[48:49], v[30:31]
	v_lshl_add_u64 v[186:187], v[170:171], 0, s[8:9]
	v_lshl_add_u64 v[188:189], v[172:173], 0, s[0:1]
	s_or_b32 s24, s30, 6
	s_add_i32 s25, s11, -1
	s_mov_b32 s48, 0
	s_mov_b32 s49, 2
	v_mov_b64_e32 v[46:47], v[28:29]
	v_mov_b64_e32 v[44:45], v[26:27]
	v_mov_b64_e32 v[42:43], v[24:25]
	v_mov_b64_e32 v[40:41], v[22:23]
	v_mov_b64_e32 v[38:39], v[20:21]
	v_mov_b64_e32 v[36:37], v[18:19]
	v_mov_b64_e32 v[34:35], v[16:17]
	ds_write2_b64 v6, v[2:3], v[4:5] offset0:128 offset1:130
	s_waitcnt lgkmcnt(0)
	s_barrier
	v_xor_b32_e32 v18, 0x80000000, v182
	v_mov_b32_e32 v19, v18
	v_mov_b32_e32 v20, v18
	v_mov_b32_e32 v21, v18
	v_mov_b32_e32 v22, v18
	v_mov_b32_e32 v23, v18
	v_mov_b32_e32 v24, v18
	v_mov_b32_e32 v25, v18
	v_mov_b32_e32 v26, v18
	v_mov_b32_e32 v27, v18
	v_mov_b32_e32 v28, v18
	v_mov_b32_e32 v29, v18
	v_mov_b32_e32 v30, v18
	v_mov_b32_e32 v31, v18
	v_mov_b32_e32 v32, v18
	v_mov_b32_e32 v33, v18
	v_readfirstlane_b32 s89, v209
	s_bfe_u32 s89, s89, 0x10002
	s_xor_b32 s89, s89, 1
	global_load_dwordx4 v[136:139], v[188:189], off
	s_and_saveexec_b64 s[0:1], s[2:3]
	s_cbranch_execz .LBB0_767

.LBB0_767:
	s_or_b64 exec, exec, s[0:1]
	global_load_dwordx4 v[132:135], v[186:187], off
	s_bitcmp1_b32 s89, 1
	s_cbranch_scc1 .LBB0_778
.Lmla_q:
	s_cmp_gt_u32 s48, s11
	s_cbranch_scc1 .LBB0_790
	s_bitcmp1_b32 s49, 0
	s_cselect_b32 s0, 0, 0x5800
	v_add_u32_e32 v16, s0, v211
	v_add_u32_e32 v16, v16, v144
	ds_read_b128 v[190:193], v16
	ds_read_b128 v[194:197], v16 offset:32
	ds_read_b128 v[222:225], v16 offset:64
	ds_read_b128 v[226:229], v16 offset:96
	ds_read_b128 v[230:233], v16 offset:128
	ds_read_b128 v[234:237], v16 offset:160
	s_cmp_lt_u32 s48, s11
	s_cbranch_scc0 .Lmla_c1only
	s_waitcnt lgkmcnt(5)
	v_mfma_f32_32x32x16_bf16 v[84:99], v[190:193], v[124:127], v[18:33]
	s_waitcnt lgkmcnt(4)
	v_mfma_f32_32x32x16_bf16 v[84:99], v[194:197], v[120:123], v[84:99]
	ds_read_b128 v[238:241], v16 offset:6656
	ds_read_b128 v[242:245], v16 offset:6688
	ds_read_b128 v[248:251], v16 offset:6720
	ds_read_b128 v[252:255], v16 offset:6752
	ds_read_b128 v[2:5], v16 offset:6784
	ds_read_b128 v[6:9], v16 offset:6816
	s_waitcnt lgkmcnt(9)
	v_mfma_f32_32x32x16_bf16 v[84:99], v[222:225], v[116:119], v[84:99]
	s_waitcnt lgkmcnt(8)
	v_mfma_f32_32x32x16_bf16 v[84:99], v[226:229], v[112:115], v[84:99]
	s_waitcnt lgkmcnt(7)
	v_mfma_f32_32x32x16_bf16 v[84:99], v[230:233], v[108:111], v[84:99]
	s_waitcnt lgkmcnt(6)
	v_mfma_f32_32x32x16_bf16 v[84:99], v[234:237], v[104:107], v[84:99]
	s_waitcnt lgkmcnt(5)
	v_mfma_f32_32x32x16_bf16 v[34:49], v[238:241], v[124:127], v[18:33]
	s_waitcnt lgkmcnt(4)
	v_mfma_f32_32x32x16_bf16 v[34:49], v[242:245], v[120:123], v[34:49]
	s_waitcnt lgkmcnt(3)
	v_mfma_f32_32x32x16_bf16 v[34:49], v[248:251], v[116:119], v[34:49]
	s_waitcnt lgkmcnt(2)
	v_mfma_f32_32x32x16_bf16 v[34:49], v[252:255], v[112:115], v[34:49]
	s_waitcnt lgkmcnt(1)
	v_mfma_f32_32x32x16_bf16 v[34:49], v[2:5], v[108:111], v[34:49]
	s_waitcnt lgkmcnt(0)
	v_mfma_f32_32x32x16_bf16 v[34:49], v[6:9], v[104:107], v[34:49]
	v_max3_i32 v16, v84, v85, v86
	v_max3_i32 v16, v16, v87, v88
	v_max3_i32 v16, v16, v89, v90
	v_max3_i32 v16, v16, v91, v92
	v_max3_i32 v16, v16, v93, v94
	v_max3_i32 v16, v16, v95, v96
	v_max3_i32 v16, v16, v97, v98
	v_max_i32_e32 v16, v16, v99
	v_add_u32_e32 v239, s0, v144
	v_add_u32_e32 v239, v239, v210
	ds_read_b128 v[190:193], v239 offset:13312
	ds_read_b128 v[194:197], v239 offset:13344
	ds_read_b128 v[222:225], v239 offset:17920
	ds_read_b128 v[226:229], v239 offset:17952
	ds_read_b128 v[10:13], v239 offset:13376
	ds_read_b128 v[230:233], v239 offset:13408
	ds_read_b128 v[100:103], v239 offset:17984
	ds_read_b128 v[234:237], v239 offset:18016
	s_or_b32 s89, s89, 4
	s_cmp_lg_u32 s25, s48
	s_cbranch_scc1 .Lmla_nomask1
	v_add_u32_e32 v239, v215, v216
	v_cmp_lt_i32_e32 vcc, -1, v239
	s_nop 1
	v_cndmask_b32_e32 v34, v218, v34, vcc
	v_cmp_lt_i32_e32 vcc, 0, v239
	s_nop 1
	v_cndmask_b32_e32 v35, v218, v35, vcc
	v_cmp_lt_i32_e32 vcc, 1, v239
	s_nop 1
	v_cndmask_b32_e32 v36, v218, v36, vcc
	v_cmp_lt_i32_e32 vcc, 2, v239
	s_nop 1
	v_cndmask_b32_e32 v37, v218, v37, vcc
	v_cmp_lt_i32_e32 vcc, 7, v239
	s_nop 1
	v_cndmask_b32_e32 v38, v218, v38, vcc
	v_cmp_lt_i32_e32 vcc, 8, v239
	s_nop 1
	v_cndmask_b32_e32 v39, v218, v39, vcc
	v_cmp_lt_i32_e32 vcc, 9, v239
	s_nop 1
	v_cndmask_b32_e32 v40, v218, v40, vcc
	v_cmp_lt_i32_e32 vcc, 10, v239
	s_nop 1
	v_cndmask_b32_e32 v41, v218, v41, vcc
	v_cmp_lt_i32_e32 vcc, 15, v239
	s_nop 1
	v_cndmask_b32_e32 v42, v218, v42, vcc
	v_cmp_lt_i32_e32 vcc, 16, v239
	s_nop 1
	v_cndmask_b32_e32 v43, v218, v43, vcc
	v_cmp_lt_i32_e32 vcc, 17, v239
	s_nop 1
	v_cndmask_b32_e32 v44, v218, v44, vcc
	v_cmp_lt_i32_e32 vcc, 18, v239
	s_nop 1
	v_cndmask_b32_e32 v45, v218, v45, vcc
	v_cmp_lt_i32_e32 vcc, 23, v239
	s_nop 1
	v_cndmask_b32_e32 v46, v218, v46, vcc
	v_cmp_lt_i32_e32 vcc, 24, v239
	s_nop 1
	v_cndmask_b32_e32 v47, v218, v47, vcc
	v_cmp_lt_i32_e32 vcc, 25, v239
	s_nop 1
	v_cndmask_b32_e32 v48, v218, v48, vcc
	v_cmp_lt_i32_e32 vcc, 26, v239
	s_nop 1
	v_cndmask_b32_e32 v49, v218, v49, vcc
.Lmla_nomask1:
	v_max3_i32 v238, v34, v35, v36
	v_max3_i32 v238, v238, v37, v38
	v_max3_i32 v238, v238, v39, v40
	v_max3_i32 v238, v238, v41, v42
	v_max3_i32 v238, v238, v43, v44
	v_max3_i32 v238, v238, v45, v46
	v_max3_i32 v238, v238, v47, v48
	v_max_i32_e32 v238, v238, v49
	v_max_i32_e32 v238, v16, v238
	s_branch .Lmla_qend
.Lmla_c1only:
	s_waitcnt lgkmcnt(5)
	v_mfma_f32_32x32x16_bf16 v[84:99], v[190:193], v[124:127], v[18:33]
	s_waitcnt lgkmcnt(4)
	v_mfma_f32_32x32x16_bf16 v[84:99], v[194:197], v[120:123], v[84:99]
	s_waitcnt lgkmcnt(3)
	v_mfma_f32_32x32x16_bf16 v[84:99], v[222:225], v[116:119], v[84:99]
	s_waitcnt lgkmcnt(2)
	v_mfma_f32_32x32x16_bf16 v[84:99], v[226:229], v[112:115], v[84:99]
	s_waitcnt lgkmcnt(1)
	v_mfma_f32_32x32x16_bf16 v[84:99], v[230:233], v[108:111], v[84:99]
	s_waitcnt lgkmcnt(0)
	v_mfma_f32_32x32x16_bf16 v[84:99], v[234:237], v[104:107], v[84:99]
	s_nop 7
	v_add_u32_e32 v16, s0, v144
	v_add_u32_e32 v16, v16, v210
	ds_read_b128 v[190:193], v16 offset:13312
	ds_read_b128 v[194:197], v16 offset:13344
	ds_read_b128 v[222:225], v16 offset:17920
	ds_read_b128 v[226:229], v16 offset:17952
	s_andn2_b32 s89, s89, 4
	s_cmp_eq_u32 s11, s48
	s_cbranch_scc0 .Lmla_nomask0
	v_add_u32_e32 v16, v215, v216
	v_cmp_lt_i32_e32 vcc, -1, v16
	s_nop 1
	v_cndmask_b32_e32 v84, v218, v84, vcc
	v_cmp_lt_i32_e32 vcc, 0, v16
	s_nop 1
	v_cndmask_b32_e32 v85, v218, v85, vcc
	v_cmp_lt_i32_e32 vcc, 1, v16
	s_nop 1
	v_cndmask_b32_e32 v86, v218, v86, vcc
	v_cmp_lt_i32_e32 vcc, 2, v16
	s_nop 1
	v_cndmask_b32_e32 v87, v218, v87, vcc
	v_cmp_lt_i32_e32 vcc, 7, v16
	s_nop 1
	v_cndmask_b32_e32 v88, v218, v88, vcc
	v_cmp_lt_i32_e32 vcc, 8, v16
	s_nop 1
	v_cndmask_b32_e32 v89, v218, v89, vcc
	v_cmp_lt_i32_e32 vcc, 9, v16
	s_nop 1
	v_cndmask_b32_e32 v90, v218, v90, vcc
	v_cmp_lt_i32_e32 vcc, 10, v16
	s_nop 1
	v_cndmask_b32_e32 v91, v218, v91, vcc
	v_cmp_lt_i32_e32 vcc, 15, v16
	s_nop 1
	v_cndmask_b32_e32 v92, v218, v92, vcc
	v_cmp_lt_i32_e32 vcc, 16, v16
	s_nop 1
	v_cndmask_b32_e32 v93, v218, v93, vcc
	v_cmp_lt_i32_e32 vcc, 17, v16
	s_nop 1
	v_cndmask_b32_e32 v94, v218, v94, vcc
	v_cmp_lt_i32_e32 vcc, 18, v16
	s_nop 1
	v_cndmask_b32_e32 v95, v218, v95, vcc
	v_cmp_lt_i32_e32 vcc, 23, v16
	s_nop 1
	v_cndmask_b32_e32 v96, v218, v96, vcc
	v_cmp_lt_i32_e32 vcc, 24, v16
	s_nop 1
	v_cndmask_b32_e32 v97, v218, v97, vcc
	v_cmp_lt_i32_e32 vcc, 25, v16
	s_nop 1
	v_cndmask_b32_e32 v98, v218, v98, vcc
	v_cmp_lt_i32_e32 vcc, 26, v16
	s_nop 1
	v_cndmask_b32_e32 v99, v218, v99, vcc
.Lmla_nomask0:
	v_max3_i32 v238, v84, v85, v86
	v_max3_i32 v238, v238, v87, v88
	v_max3_i32 v238, v238, v89, v90
	v_max3_i32 v238, v238, v91, v92
	v_max3_i32 v238, v238, v93, v94
	v_max3_i32 v238, v238, v95, v96
	v_max3_i32 v238, v238, v97, v98
	v_max_i32_e32 v238, v238, v99
.Lmla_qend:
	s_bitcmp1_b32 s89, 0
	s_cbranch_scc0 .LBB0_778
	s_or_b32 s89, s89, 2
	s_branch .LBB0_790
.LBB0_778:
	s_bitcmp1_b32 s89, 2
	s_cselect_b64 s[80:81], 0, exec
	v_cmp_lt_f32_e32 vcc, s47, v238
	s_cbranch_vccz .LBB0_785
	v_max3_f32 v16, v84, s86, v85
	v_max3_f32 v16, v16, v86, v87
	v_max3_f32 v16, v16, v88, v89
	v_max3_f32 v16, v16, v90, v91
	v_max3_f32 v16, v16, v92, v93
	v_max3_f32 v16, v16, v94, v95
	v_max3_f32 v16, v16, v96, v97
	s_and_b64 vcc, exec, s[80:81]
	v_max3_f32 v16, v16, v98, v99
	s_cbranch_vccnz .LBB0_781
	v_max3_f32 v16, v16, v34, v35
	v_max3_f32 v16, v16, v36, v37
	v_max3_f32 v16, v16, v38, v39
	v_max3_f32 v16, v16, v40, v41
	v_max3_f32 v16, v16, v42, v43
	v_max3_f32 v16, v16, v44, v45
	v_max3_f32 v16, v16, v46, v47
	v_max3_f32 v16, v16, v48, v49

.LBB0_789:
	v_add_f32_e32 v16, v238, v239
	v_add_f32_e32 v183, v183, v16
	s_bitcmp1_b32 s89, 1
	s_cbranch_scc0 .LBB0_790
	s_andn2_b32 s89, s89, 2
	s_bitcmp1_b32 s89, 3
	s_cbranch_scc0 .Lmla_q
	s_andn2_b32 s89, s89, 8
	s_branch .LBB0_794

.Lmla_exit:
	s_bitcmp1_b32 s89, 1
	s_cbranch_scc0 .LBB0_794
	s_or_b32 s89, s89, 8
	s_branch .LBB0_778
